# strategy 7.12 shorten the wave-uniform work-flag test: v_cndmask+v_cmp_ne bool round trips in the layer 0/3 pair loops replaced by one s_andn2_b64
# speedup vs baseline: 1.0017x; 1.0017x over previous
; #define LAS __attribute__((address_space(3)))
;     ...
;     auto QK = [&](const LAS unsigned char* sbase, f32x16& s0, f32x16& s1) {
;         const LAS unsigned char* kb = sbase + r32 * KSTR; const int kc0 = (koff >> 3) + hi;
; #pragma unroll
;         for (int r = 0; r < 16; ++r) { s0[r] = 0.f; s1[r] = 0.f; }
; #pragma unroll
;         for (int kh = 0; kh < NKS; kh += 4) {
;             bf16x8 ka[4][2];
; #pragma unroll
;             for (int ks = 0; ks < 4; ++ks) { const int ko = ((kc0 + 2 * (kh + ks)) ^ ksw) << 4; ka[ks][0] = *(const LAS bf16x8*)(kb + ko); ka[ks][1] = *(const LAS bf16x8*)(kb + 32 * KSTR + ko); }
;             __builtin_amdgcn_s_setprio(1);
; #pragma unroll
;             for (int ks = 0; ks < 4; ++ks) { s0 = __builtin_amdgcn_mfma_f32_32x32x16_bf16(ka[ks][0], qf[kh + ks], s0, 0, 0, 0); s1 = __builtin_amdgcn_mfma_f32_32x32x16_bf16(ka[ks][1], qf[kh + ks], s1, 0, 0, 0); }
;             __builtin_amdgcn_s_setprio(0);
;         }
;     };
;     ...
;             const bool wka = active && !(dual && hsel) && ta <= my_last && !(xmode & 1), wkb = active && !(dual && !hsel) && tb < u.ntiles && tb <= my_last && !(xmode & 1);
;             f32x16 a0, a1, b0, b1; bf16x8 pba[2][2], pbb[2][2]; s16x4 vpre[4][2], va[4][2], vbb[4][2];
;             unsigned wa0 = 0xffffffffu, wa1 = 0xffffffffu, wb0 = 0xffffffffu, wb1 = 0xffffffffu;
;             if (LAYER == 1) { const v2u ma = *(const LAS v2u*)(sa + 2 * STAGEB + (32 * sb + r32) * 8), mb = *(const LAS v2u*)(sa + 2 * STAGEB + MSKB + (32 * sb + r32) * 8); wa0 = ma.x; wa1 = ma.y; wb0 = mb.x; wb1 = mb.y; }
;             if (wka) QK(sa, a0, a1);
;             if (LAYER == 0) { if (wkb) QK(sbb, b0, b1); }
.LBB0_584:
	s_add_i32 s2, s74, 1
	s_cmp_lt_u32 s2, s75
	s_cselect_b64 s[2:3], -1, 0
	s_cmp_lt_u32 s74, s9
	s_cselect_b64 s[30:31], -1, 0
	s_and_b64 s[30:31], s[2:3], s[30:31]
	s_andn2_b64 s[2:3], exec, s[30:31]
	s_andn2_b64 vcc, exec, s[30:31]
	s_cbranch_vccnz .LBB0_586
	ds_read_b128 v[84:87], v151 offset:32768
	ds_read_b128 v[116:119], v151 offset:40960
	ds_read_b128 v[152:155], v150 offset:32768
	ds_read_b128 v[156:159], v150 offset:40960
	ds_read_b128 v[160:163], v149 offset:32768
	ds_read_b128 v[200:203], v149 offset:40960
	ds_read_b128 v[204:207], v148 offset:32768
	ds_read_b128 v[148:151], v148 offset:40960
	s_nop 0
	s_waitcnt lgkmcnt(0)
	v_mfma_f32_32x32x16_bf16 v[84:99], v[84:87], v[132:135], 0
	v_mfma_f32_32x32x16_bf16 v[116:131], v[116:119], v[132:135], 0
	v_mfma_f32_32x32x16_bf16 v[84:99], v[152:155], v[136:139], v[84:99]
	v_mfma_f32_32x32x16_bf16 v[116:131], v[156:159], v[136:139], v[116:131]
	v_mfma_f32_32x32x16_bf16 v[84:99], v[160:163], v[140:143], v[84:99]
	v_mfma_f32_32x32x16_bf16 v[116:131], v[200:203], v[140:143], v[116:131]
	v_mfma_f32_32x32x16_bf16 v[84:99], v[204:207], v[144:147], v[84:99]
	v_mfma_f32_32x32x16_bf16 v[116:131], v[148:151], v[144:147], v[116:131]
	s_nop 0

; #define LAS __attribute__((address_space(3)))
;     ...
;     auto QK = [&](const LAS unsigned char* sbase, f32x16& s0, f32x16& s1) {
;         const LAS unsigned char* kb = sbase + r32 * KSTR; const int kc0 = (koff >> 3) + hi;
; #pragma unroll
;         for (int r = 0; r < 16; ++r) { s0[r] = 0.f; s1[r] = 0.f; }
; #pragma unroll
;         for (int kh = 0; kh < NKS; kh += 4) {
;             bf16x8 ka[4][2];
; #pragma unroll
;             for (int ks = 0; ks < 4; ++ks) { const int ko = ((kc0 + 2 * (kh + ks)) ^ ksw) << 4; ka[ks][0] = *(const LAS bf16x8*)(kb + ko); ka[ks][1] = *(const LAS bf16x8*)(kb + 32 * KSTR + ko); }
;             __builtin_amdgcn_s_setprio(1);
; #pragma unroll
;             for (int ks = 0; ks < 4; ++ks) { s0 = __builtin_amdgcn_mfma_f32_32x32x16_bf16(ka[ks][0], qf[kh + ks], s0, 0, 0, 0); s1 = __builtin_amdgcn_mfma_f32_32x32x16_bf16(ka[ks][1], qf[kh + ks], s1, 0, 0, 0); }
;             __builtin_amdgcn_s_setprio(0);
;         }
;     };
;     ...
;             LAS unsigned char* const sa = lds + (p & 1) * STG2; LAS unsigned char* const sbb = sa + STAGEB;
;             const int ta = dual ? p : 2 * p, tb = dual ? p : 2 * p + 1;
;             const bool wka = active && !(dual && hsel) && ta <= my_last && !(xmode & 1), wkb = active && !(dual && !hsel) && tb < u.ntiles && tb <= my_last && !(xmode & 1);
;             f32x16 a0, a1, b0, b1; bf16x8 pba[2][2], pbb[2][2]; s16x4 vpre[4][2], va[4][2], vbb[4][2];
;             unsigned wa0 = 0xffffffffu, wa1 = 0xffffffffu, wb0 = 0xffffffffu, wb1 = 0xffffffffu;
;             if (LAYER == 1) { const v2u ma = *(const LAS v2u*)(sa + 2 * STAGEB + (32 * sb + r32) * 8), mb = *(const LAS v2u*)(sa + 2 * STAGEB + MSKB + (32 * sb + r32) * 8); wa0 = ma.x; wa1 = ma.y; wb0 = mb.x; wb1 = mb.y; }
;             if (wka) QK(sa, a0, a1);
;             if (LAYER == 0) { if (wkb) QK(sbb, b0, b1); }
.LBB0_3316:
	s_bitcmp1_b32 s97, 0
	s_cselect_b32 s2, 0x10400, 0
	s_add_i32 s45, s2, 0
	s_add_i32 s4, s94, -1
	s_and_b64 s[2:3], s[24:25], exec
	s_cselect_b32 s2, s4, s97
	s_cmp_le_u32 s2, s91
	s_cselect_b64 s[2:3], -1, 0
	s_and_b64 s[2:3], s[28:29], s[2:3]
	s_andn2_b64 s[4:5], exec, s[2:3]
	v_add_u32_e32 v146, s45, v196
	s_andn2_b64 vcc, exec, s[2:3]
	v_add_u32_e32 v149, v146, v197
	v_add_u32_e32 v148, v146, v198
	v_add_u32_e32 v147, v146, v199
	v_add_u32_e32 v146, v146, v200
	s_cbranch_vccnz .LBB0_3318
	ds_read_b128 v[66:69], v149
	ds_read_b128 v[98:101], v149 offset:8192
	ds_read_b128 v[150:153], v148
	ds_read_b128 v[154:157], v148 offset:8192
	ds_read_b128 v[158:161], v147
	ds_read_b128 v[202:205], v147 offset:8192
	ds_read_b128 v[206:209], v146
	ds_read_b128 v[210:213], v146 offset:8192
	s_nop 0
	s_waitcnt lgkmcnt(0)
	v_mfma_f32_32x32x16_bf16 v[66:81], v[66:69], v[130:133], 0
	v_mfma_f32_32x32x16_bf16 v[98:113], v[98:101], v[130:133], 0
	v_mfma_f32_32x32x16_bf16 v[66:81], v[150:153], v[134:137], v[66:81]
	v_mfma_f32_32x32x16_bf16 v[98:113], v[154:157], v[134:137], v[98:113]
	v_mfma_f32_32x32x16_bf16 v[66:81], v[158:161], v[138:141], v[66:81]
	v_mfma_f32_32x32x16_bf16 v[98:113], v[202:205], v[138:141], v[98:113]
	v_mfma_f32_32x32x16_bf16 v[66:81], v[206:209], v[142:145], v[66:81]
	v_mfma_f32_32x32x16_bf16 v[98:113], v[210:213], v[142:145], v[98:113]
	s_nop 0
.LBB0_3318:
	s_and_b64 s[2:3], s[24:25], exec
	s_cselect_b32 s48, s94, s97
	s_cmp_lt_i32 s48, s89
	s_cselect_b64 s[2:3], -1, 0
	s_and_b64 s[2:3], s[30:31], s[2:3]
	s_cmp_le_u32 s48, s91
	s_cselect_b64 s[48:49], -1, 0
	s_and_b64 s[48:49], s[2:3], s[48:49]
	s_andn2_b64 s[2:3], exec, s[48:49]
	s_andn2_b64 vcc, exec, s[48:49]
	s_cbranch_vccnz .LBB0_3320
	ds_read_b128 v[82:85], v149 offset:32768
	ds_read_b128 v[114:117], v149 offset:40960
	ds_read_b128 v[150:153], v148 offset:32768
	ds_read_b128 v[154:157], v148 offset:40960
	ds_read_b128 v[158:161], v147 offset:32768
	ds_read_b128 v[202:205], v147 offset:40960
	ds_read_b128 v[206:209], v146 offset:32768
	ds_read_b128 v[146:149], v146 offset:40960
	s_nop 0
	s_waitcnt lgkmcnt(0)
	v_mfma_f32_32x32x16_bf16 v[82:97], v[82:85], v[130:133], 0
	v_mfma_f32_32x32x16_bf16 v[114:129], v[114:117], v[130:133], 0
	v_mfma_f32_32x32x16_bf16 v[82:97], v[150:153], v[134:137], v[82:97]
	v_mfma_f32_32x32x16_bf16 v[114:129], v[154:157], v[134:137], v[114:129]
	v_mfma_f32_32x32x16_bf16 v[82:97], v[158:161], v[138:141], v[82:97]
	v_mfma_f32_32x32x16_bf16 v[114:129], v[202:205], v[138:141], v[114:129]
	v_mfma_f32_32x32x16_bf16 v[82:97], v[206:209], v[142:145], v[82:97]
	v_mfma_f32_32x32x16_bf16 v[114:129], v[146:149], v[142:145], v[114:129]
	s_nop 0
